# UG tile stores with nt hint (consumed two phases later)
# speedup vs baseline: 1.0265x; 1.0024x over previous
; #define PG8_STAGE(bufoff, gbase, voff) do { _Pragma("unroll") for (int _i = 0; _i < 2; ++_i) \
;         __builtin_amdgcn_global_load_lds((const __attribute__((address_space(1))) unsigned*)((const char*)(gbase) + (voff)[_i]), (LAS unsigned*)(lds + (bufoff) + ldsw + _i * 8192), 16, 0, 0); } while (0)
; #define PG8_LDA(dst, b, h) do { _Pragma("unroll") for (int m = 0; m < 4; ++m) _Pragma("unroll") for (int k = 0; k < 2; ++k) dst[m][k] = *(const LAS bf16x8*)(lds + PG8_SA(b, h) + aoff + m * 2048 + k * 1024); } while (0)
; #define PG8_LDB(dst, b, h) do { _Pragma("unroll") for (int n = 0; n < 2; ++n) _Pragma("unroll") for (int k = 0; k < 2; ++k) dst[n][k] = *(const LAS bf16x8*)(lds + PG8_SB(b, h) + boff + n * 2048 + k * 1024); } while (0)
; #define PG8_MMA(ai, bj, At, Bt) do { __builtin_amdgcn_s_setprio(1); _Pragma("unroll") for (int m = 0; m < 4; ++m) _Pragma("unroll") for (int n = 0; n < 2; ++n) _Pragma("unroll") for (int k = 0; k < 2; ++k) \
;         acc[ai][bj][m][n] = __builtin_amdgcn_mfma_f32_16x16x32_bf16(Bt[n][k], At[m][k], acc[ai][bj][m][n], 0, 0, 0); __builtin_amdgcn_s_setprio(0); } while (0)
; #define PG8_WAIT_L(n) asm volatile("s_waitcnt lgkmcnt(" #n ")" ::: "memory")
; #define PG8_BAR __builtin_amdgcn_s_barrier()
; #define PG8_SCHED __builtin_amdgcn_sched_barrier(0)
; template <class Epi>
; __device__ __forceinline__ void gemm_phase(LAS unsigned char* lds, const Gemm g, const StaticOrder& S_in, const Epi& E, int sw) {
;     ...
;             PG8_LDB(B0, 0, 0); PG8_SCHED; PG8_LDA(At, 0, 0); PG8_STAGE(PG8_SA(1, 1), a1 + hstepA, voffA);
;             PG8_WAIT_L(8); PG8_BAR; PG8_WAIT_L(0); PG8_MMA(0, 0, At, B0); PG8_BAR; PG8_SCHED;
;             PG8_LDB(B1, 0, 1); PG8_STAGE(PG8_SB(0, 0), b2, voffB);
;             PG8_BAR; PG8_WAIT_L(0); PG8_MMA(0, 1, At, B1); PG8_BAR;
;             PG8_LDA(At, 0, 1); PG8_STAGE(PG8_SA(0, 0), a2, voffA);
;             PG8_BAR; PG8_WAIT_L(0); PG8_MMA(1, 0, At, B0); PG8_BAR; PG8_SCHED;
.LBB0_756:
	s_add_u32 s26, s24, 0xfffc0080
	s_addc_u32 s27, s25, -1
	s_add_i32 s56, 0, 0x10000
	v_add_u32_e32 v140, s56, v142
	ds_read_b128 v[144:147], v140
	ds_read_b128 v[148:151], v140 offset:1024
	ds_read_b128 v[152:155], v140 offset:2048
	ds_read_b128 v[156:159], v140 offset:3072
	s_cmp_eq_u32 s55, 12
	s_cselect_b32 s29, s17, s27
	s_cselect_b32 s28, s51, s26
	s_cselect_b32 s27, s13, s54
	s_cselect_b32 s26, s52, s53
	v_lshl_add_u64 v[140:141], s[24:25], 0, v[136:137]
	s_add_i32 m0, s23, 0xc000
	ds_read_b128 v[160:163], v143
	ds_read_b128 v[164:167], v143 offset:1024
	ds_read_b128 v[172:175], v143 offset:2048
	ds_read_b128 v[176:179], v143 offset:3072
	ds_read_b128 v[180:183], v143 offset:4096
	ds_read_b128 v[184:187], v143 offset:5120
	ds_read_b128 v[188:191], v143 offset:6144
	ds_read_b128 v[192:195], v143 offset:7168
	global_load_lds_dwordx4 v[140:141], off
	v_lshl_add_u64 v[140:141], s[24:25], 0, v[138:139]
	s_add_i32 m0, s23, 0xe000
	s_nop 0
	global_load_lds_dwordx4 v[140:141], off
	s_waitcnt lgkmcnt(8)
	s_barrier
	s_waitcnt lgkmcnt(0)
	s_setprio 1
	s_waitcnt lgkmcnt(0)
	v_mfma_f32_16x16x32_bf16 v[126:129], v[144:147], v[160:163], v[126:129]
	v_mfma_f32_16x16x32_bf16 v[118:121], v[152:155], v[160:163], v[118:121]
	v_mfma_f32_16x16x32_bf16 v[110:113], v[144:147], v[172:175], v[110:113]
	v_mfma_f32_16x16x32_bf16 v[102:105], v[152:155], v[172:175], v[102:105]
	v_mfma_f32_16x16x32_bf16 v[94:97], v[144:147], v[180:183], v[94:97]
	v_mfma_f32_16x16x32_bf16 v[86:89], v[152:155], v[180:183], v[86:89]
	v_mfma_f32_16x16x32_bf16 v[78:81], v[144:147], v[188:191], v[78:81]
	v_mfma_f32_16x16x32_bf16 v[70:73], v[152:155], v[188:191], v[70:73]
	v_mfma_f32_16x16x32_bf16 v[126:129], v[148:151], v[164:167], v[126:129]
	v_mfma_f32_16x16x32_bf16 v[118:121], v[156:159], v[164:167], v[118:121]
	v_mfma_f32_16x16x32_bf16 v[110:113], v[148:151], v[176:179], v[110:113]
	v_mfma_f32_16x16x32_bf16 v[102:105], v[156:159], v[176:179], v[102:105]
	v_mfma_f32_16x16x32_bf16 v[94:97], v[148:151], v[184:187], v[94:97]
	v_mfma_f32_16x16x32_bf16 v[86:89], v[156:159], v[184:187], v[86:89]
	v_mfma_f32_16x16x32_bf16 v[78:81], v[148:151], v[192:195], v[78:81]
	v_mfma_f32_16x16x32_bf16 v[70:73], v[156:159], v[192:195], v[70:73]
	s_setprio 0
	s_barrier
	s_add_i32 s58, 0, 0x14000
	v_add_u32_e32 v140, s58, v142
	s_add_i32 s56, s56, s41
	ds_read_b128 v[196:199], v140
	ds_read_b128 v[200:203], v140 offset:1024
	ds_read_b128 v[204:207], v140 offset:2048
	ds_read_b128 v[208:211], v140 offset:3072
	v_lshl_add_u64 v[140:141], s[26:27], 0, v[0:1]
	s_mov_b32 m0, s56
	v_lshl_add_u64 v[168:169], s[26:27], 0, v[130:131]
	global_load_lds_dwordx4 v[140:141], off
	s_add_i32 m0, s56, 0x2000
	s_nop 0
	global_load_lds_dwordx4 v[168:169], off
	s_barrier
	s_waitcnt lgkmcnt(0)
	s_setprio 1
	s_waitcnt lgkmcnt(0)
	v_mfma_f32_16x16x32_bf16 v[122:125], v[196:199], v[160:163], v[122:125]
	v_mfma_f32_16x16x32_bf16 v[114:117], v[204:207], v[160:163], v[114:117]
	v_mfma_f32_16x16x32_bf16 v[106:109], v[196:199], v[172:175], v[106:109]
	v_mfma_f32_16x16x32_bf16 v[98:101], v[204:207], v[172:175], v[98:101]
	v_mfma_f32_16x16x32_bf16 v[90:93], v[196:199], v[180:183], v[90:93]
	v_mfma_f32_16x16x32_bf16 v[82:85], v[204:207], v[180:183], v[82:85]
	v_mfma_f32_16x16x32_bf16 v[74:77], v[196:199], v[188:191], v[74:77]
	v_mfma_f32_16x16x32_bf16 v[66:69], v[204:207], v[188:191], v[66:69]
	v_mfma_f32_16x16x32_bf16 v[122:125], v[200:203], v[164:167], v[122:125]
	v_mfma_f32_16x16x32_bf16 v[114:117], v[208:211], v[164:167], v[114:117]
	v_mfma_f32_16x16x32_bf16 v[106:109], v[200:203], v[176:179], v[106:109]
	v_mfma_f32_16x16x32_bf16 v[98:101], v[208:211], v[176:179], v[98:101]
	v_mfma_f32_16x16x32_bf16 v[90:93], v[200:203], v[184:187], v[90:93]
	v_mfma_f32_16x16x32_bf16 v[82:85], v[208:211], v[184:187], v[82:85]
	v_mfma_f32_16x16x32_bf16 v[74:77], v[200:203], v[192:195], v[74:77]
	v_mfma_f32_16x16x32_bf16 v[66:69], v[208:211], v[192:195], v[66:69]
	s_setprio 0
	s_mov_b32 m0, s23
	v_lshl_add_u64 v[212:213], s[28:29], 0, v[134:135]
	s_barrier
	ds_read_b128 v[160:163], v143 offset:16384
	ds_read_b128 v[164:167], v143 offset:17408
	ds_read_b128 v[172:175], v143 offset:18432
	ds_read_b128 v[176:179], v143 offset:19456
	ds_read_b128 v[180:183], v143 offset:20480
	ds_read_b128 v[184:187], v143 offset:21504
	ds_read_b128 v[188:191], v143 offset:22528
	ds_read_b128 v[192:195], v143 offset:23552
	global_load_lds_dwordx4 v[212:213], off
	v_lshl_add_u64 v[214:215], s[28:29], 0, v[132:133]
	s_mov_b32 m0, s43
	s_nop 0
	global_load_lds_dwordx4 v[214:215], off
	s_barrier
	s_waitcnt lgkmcnt(0)
	s_setprio 1
	s_waitcnt lgkmcnt(0)
	v_mfma_f32_16x16x32_bf16 v[62:65], v[144:147], v[160:163], v[62:65]
	v_mfma_f32_16x16x32_bf16 v[54:57], v[152:155], v[160:163], v[54:57]
	v_mfma_f32_16x16x32_bf16 v[46:49], v[144:147], v[172:175], v[46:49]
	v_mfma_f32_16x16x32_bf16 v[38:41], v[152:155], v[172:175], v[38:41]
	v_mfma_f32_16x16x32_bf16 v[30:33], v[144:147], v[180:183], v[30:33]
	v_mfma_f32_16x16x32_bf16 v[22:25], v[152:155], v[180:183], v[22:25]
	v_mfma_f32_16x16x32_bf16 v[14:17], v[144:147], v[188:191], v[14:17]
	v_mfma_f32_16x16x32_bf16 v[6:9], v[152:155], v[188:191], v[6:9]
	v_mfma_f32_16x16x32_bf16 v[62:65], v[148:151], v[164:167], v[62:65]
	v_mfma_f32_16x16x32_bf16 v[54:57], v[156:159], v[164:167], v[54:57]
	v_mfma_f32_16x16x32_bf16 v[46:49], v[148:151], v[176:179], v[46:49]
	v_mfma_f32_16x16x32_bf16 v[38:41], v[156:159], v[176:179], v[38:41]
	v_mfma_f32_16x16x32_bf16 v[30:33], v[148:151], v[184:187], v[30:33]
	v_mfma_f32_16x16x32_bf16 v[22:25], v[156:159], v[184:187], v[22:25]
	v_mfma_f32_16x16x32_bf16 v[14:17], v[148:151], v[192:195], v[14:17]
	v_mfma_f32_16x16x32_bf16 v[6:9], v[156:159], v[192:195], v[6:9]
	s_setprio 0
	s_barrier
; #define PG8_STAGE(bufoff, gbase, voff) do { _Pragma("unroll") for (int _i = 0; _i < 2; ++_i) \
;         __builtin_amdgcn_global_load_lds((const __attribute__((address_space(1))) unsigned*)((const char*)(gbase) + (voff)[_i]), (LAS unsigned*)(lds + (bufoff) + ldsw + _i * 8192), 16, 0, 0); } while (0)
; #define PG8_LDA(dst, b, h) do { _Pragma("unroll") for (int m = 0; m < 4; ++m) _Pragma("unroll") for (int k = 0; k < 2; ++k) dst[m][k] = *(const LAS bf16x8*)(lds + PG8_SA(b, h) + aoff + m * 2048 + k * 1024); } while (0)
; #define PG8_LDB(dst, b, h) do { _Pragma("unroll") for (int n = 0; n < 2; ++n) _Pragma("unroll") for (int k = 0; k < 2; ++k) dst[n][k] = *(const LAS bf16x8*)(lds + PG8_SB(b, h) + boff + n * 2048 + k * 1024); } while (0)
; #define PG8_MMA(ai, bj, At, Bt) do { __builtin_amdgcn_s_setprio(1); _Pragma("unroll") for (int m = 0; m < 4; ++m) _Pragma("unroll") for (int n = 0; n < 2; ++n) _Pragma("unroll") for (int k = 0; k < 2; ++k) \
;         acc[ai][bj][m][n] = __builtin_amdgcn_mfma_f32_16x16x32_bf16(Bt[n][k], At[m][k], acc[ai][bj][m][n], 0, 0, 0); __builtin_amdgcn_s_setprio(0); } while (0)
; #define PG8_WAIT_V(n) asm volatile("s_waitcnt vmcnt(" #n ")" ::: "memory")
; #define PG8_WAIT_L(n) asm volatile("s_waitcnt lgkmcnt(" #n ")" ::: "memory")
; #define PG8_BAR __builtin_amdgcn_s_barrier()
; #define PG8_SCHED __builtin_amdgcn_sched_barrier(0)
; template <class Epi>
; __device__ __forceinline__ void gemm_phase(LAS unsigned char* lds, const Gemm g, const StaticOrder& S_in, const Epi& E, int sw) {
;     ...
;             PG8_STAGE(PG8_SB(0, 1), b2 + hstepB, voffB);
;             PG8_WAIT_V(6); PG8_BAR; PG8_MMA(1, 1, At, B1); PG8_BAR;
;             PG8_LDB(B0, 1, 0); PG8_SCHED; PG8_LDA(At, 1, 0); PG8_STAGE(PG8_SA(0, 1), a2 + hstepA, voffA);
;             PG8_WAIT_L(8); PG8_BAR; PG8_WAIT_L(0); PG8_MMA(0, 0, At, B0); PG8_BAR; PG8_SCHED;
;             PG8_LDB(B1, 1, 1); PG8_STAGE(PG8_SB(1, 0), b3, voffB);
;             PG8_BAR; PG8_WAIT_L(0); PG8_MMA(0, 1, At, B1); PG8_BAR;
;             PG8_LDA(At, 1, 1); PG8_STAGE(PG8_SA(1, 0), a3, voffA);
;             PG8_BAR; PG8_WAIT_L(0); PG8_MMA(1, 0, At, B0); PG8_BAR; PG8_SCHED;
	s_add_u32 s56, s26, 0x40000
	s_addc_u32 s57, s27, 0
	s_add_i32 s58, s58, s41
	v_lshl_add_u64 v[144:145], s[56:57], 0, v[0:1]
	s_mov_b32 m0, s58
	s_nop 0
	global_load_lds_dwordx4 v[144:145], off
	v_lshl_add_u64 v[144:145], s[56:57], 0, v[130:131]
	s_add_i32 m0, s58, 0x2000
	s_nop 0
	global_load_lds_dwordx4 v[144:145], off
	s_waitcnt vmcnt(6)
	s_barrier
	s_setprio 1
	v_mfma_f32_16x16x32_bf16 v[58:61], v[196:199], v[160:163], v[58:61]
	v_mfma_f32_16x16x32_bf16 v[50:53], v[204:207], v[160:163], v[50:53]
	v_mfma_f32_16x16x32_bf16 v[42:45], v[196:199], v[172:175], v[42:45]
	v_mfma_f32_16x16x32_bf16 v[34:37], v[204:207], v[172:175], v[34:37]
	v_mfma_f32_16x16x32_bf16 v[26:29], v[196:199], v[180:183], v[26:29]
	v_mfma_f32_16x16x32_bf16 v[18:21], v[204:207], v[180:183], v[18:21]
	v_mfma_f32_16x16x32_bf16 v[10:13], v[196:199], v[188:191], v[10:13]
	v_mfma_f32_16x16x32_bf16 v[2:5], v[204:207], v[188:191], v[2:5]
	v_mfma_f32_16x16x32_bf16 v[58:61], v[200:203], v[164:167], v[58:61]
	v_mfma_f32_16x16x32_bf16 v[50:53], v[208:211], v[164:167], v[50:53]
	v_mfma_f32_16x16x32_bf16 v[42:45], v[200:203], v[176:179], v[42:45]
	v_mfma_f32_16x16x32_bf16 v[34:37], v[208:211], v[176:179], v[34:37]
	v_mfma_f32_16x16x32_bf16 v[26:29], v[200:203], v[184:187], v[26:29]
	v_mfma_f32_16x16x32_bf16 v[18:21], v[208:211], v[184:187], v[18:21]
	v_mfma_f32_16x16x32_bf16 v[10:13], v[200:203], v[192:195], v[10:13]
	v_mfma_f32_16x16x32_bf16 v[2:5], v[208:211], v[192:195], v[2:5]
	s_setprio 0
	s_add_i32 s56, 0, 0x18000
	v_add_u32_e32 v156, s56, v142
	s_barrier
	ds_read_b128 v[144:147], v156
	ds_read_b128 v[148:151], v156 offset:1024
	ds_read_b128 v[152:155], v156 offset:2048
	ds_read_b128 v[156:159], v156 offset:3072
	s_add_u32 s28, s28, 0x40000
	s_addc_u32 s29, s29, 0
	s_mov_b32 m0, s44
	v_lshl_add_u64 v[196:197], s[28:29], 0, v[134:135]
	ds_read_b128 v[160:163], v143 offset:32768
	ds_read_b128 v[164:167], v143 offset:33792
	ds_read_b128 v[172:175], v143 offset:34816
	ds_read_b128 v[176:179], v143 offset:35840
	ds_read_b128 v[180:183], v143 offset:36864
	ds_read_b128 v[184:187], v143 offset:37888
	ds_read_b128 v[188:191], v143 offset:38912
	ds_read_b128 v[192:195], v143 offset:39936
	global_load_lds_dwordx4 v[196:197], off
	v_lshl_add_u64 v[196:197], s[28:29], 0, v[132:133]
	s_mov_b32 m0, s45
	s_nop 0
	global_load_lds_dwordx4 v[196:197], off
	s_waitcnt lgkmcnt(8)
	s_barrier
	s_waitcnt lgkmcnt(0)
	s_setprio 1
	s_waitcnt lgkmcnt(0)
	v_mfma_f32_16x16x32_bf16 v[126:129], v[144:147], v[160:163], v[126:129]
	v_mfma_f32_16x16x32_bf16 v[118:121], v[152:155], v[160:163], v[118:121]
	v_mfma_f32_16x16x32_bf16 v[110:113], v[144:147], v[172:175], v[110:113]
	v_mfma_f32_16x16x32_bf16 v[102:105], v[152:155], v[172:175], v[102:105]
	v_mfma_f32_16x16x32_bf16 v[94:97], v[144:147], v[180:183], v[94:97]
	v_mfma_f32_16x16x32_bf16 v[86:89], v[152:155], v[180:183], v[86:89]
	v_mfma_f32_16x16x32_bf16 v[78:81], v[144:147], v[188:191], v[78:81]
	v_mfma_f32_16x16x32_bf16 v[70:73], v[152:155], v[188:191], v[70:73]
	v_mfma_f32_16x16x32_bf16 v[126:129], v[148:151], v[164:167], v[126:129]
	v_mfma_f32_16x16x32_bf16 v[118:121], v[156:159], v[164:167], v[118:121]
	v_mfma_f32_16x16x32_bf16 v[110:113], v[148:151], v[176:179], v[110:113]
	v_mfma_f32_16x16x32_bf16 v[102:105], v[156:159], v[176:179], v[102:105]
	v_mfma_f32_16x16x32_bf16 v[94:97], v[148:151], v[184:187], v[94:97]
	v_mfma_f32_16x16x32_bf16 v[86:89], v[156:159], v[184:187], v[86:89]
	v_mfma_f32_16x16x32_bf16 v[78:81], v[148:151], v[192:195], v[78:81]
	v_mfma_f32_16x16x32_bf16 v[70:73], v[156:159], v[192:195], v[70:73]
	s_setprio 0
	s_barrier
	s_add_i32 s28, 0, 0x1c000
	s_add_i32 s29, s56, s41
	v_add_u32_e32 v171, s28, v142
	v_lshl_add_u64 v[140:141], v[140:141], 0, s[86:87]
	s_mov_b32 m0, s29
	ds_read_b128 v[196:199], v171
	ds_read_b128 v[200:203], v171 offset:1024
	ds_read_b128 v[204:207], v171 offset:2048
	ds_read_b128 v[208:211], v171 offset:3072
	global_load_lds_dwordx4 v[140:141], off
	v_lshl_add_u64 v[140:141], v[168:169], 0, s[86:87]
	s_add_i32 m0, s29, 0x2000
	s_nop 0
	global_load_lds_dwordx4 v[140:141], off
	s_barrier
	s_waitcnt lgkmcnt(0)
	s_setprio 1
	s_waitcnt lgkmcnt(0)
	v_mfma_f32_16x16x32_bf16 v[122:125], v[196:199], v[160:163], v[122:125]
	v_mfma_f32_16x16x32_bf16 v[114:117], v[204:207], v[160:163], v[114:117]
	v_mfma_f32_16x16x32_bf16 v[106:109], v[196:199], v[172:175], v[106:109]
	v_mfma_f32_16x16x32_bf16 v[98:101], v[204:207], v[172:175], v[98:101]
	v_mfma_f32_16x16x32_bf16 v[90:93], v[196:199], v[180:183], v[90:93]
	v_mfma_f32_16x16x32_bf16 v[82:85], v[204:207], v[180:183], v[82:85]
	v_mfma_f32_16x16x32_bf16 v[74:77], v[196:199], v[188:191], v[74:77]
	v_mfma_f32_16x16x32_bf16 v[66:69], v[204:207], v[188:191], v[66:69]
	v_mfma_f32_16x16x32_bf16 v[122:125], v[200:203], v[164:167], v[122:125]
	v_mfma_f32_16x16x32_bf16 v[114:117], v[208:211], v[164:167], v[114:117]
	v_mfma_f32_16x16x32_bf16 v[106:109], v[200:203], v[176:179], v[106:109]
	v_mfma_f32_16x16x32_bf16 v[98:101], v[208:211], v[176:179], v[98:101]
	v_mfma_f32_16x16x32_bf16 v[90:93], v[200:203], v[184:187], v[90:93]
	v_mfma_f32_16x16x32_bf16 v[82:85], v[208:211], v[184:187], v[82:85]
	v_mfma_f32_16x16x32_bf16 v[74:77], v[200:203], v[192:195], v[74:77]
	v_mfma_f32_16x16x32_bf16 v[66:69], v[208:211], v[192:195], v[66:69]
	s_setprio 0
	s_mov_b32 m0, s46
	v_lshl_add_u64 v[140:141], v[212:213], 0, s[86:87]
	s_barrier
	ds_read_b128 v[160:163], v143 offset:49152
	ds_read_b128 v[164:167], v143 offset:50176
	ds_read_b128 v[172:175], v143 offset:51200
	ds_read_b128 v[176:179], v143 offset:52224
	ds_read_b128 v[180:183], v143 offset:53248
	ds_read_b128 v[184:187], v143 offset:54272
	ds_read_b128 v[188:191], v143 offset:55296
	ds_read_b128 v[192:195], v143 offset:56320
	global_load_lds_dwordx4 v[140:141], off
	v_lshl_add_u64 v[140:141], v[214:215], 0, s[86:87]
	s_mov_b32 m0, s47
	s_nop 0
	global_load_lds_dwordx4 v[140:141], off
	s_barrier
; __device__ __forceinline__ int ltid(int sw) { unsigned z = 0u; asm volatile("" : "+s"(sw), "+s"(z)); int t = sw * 64 + (int)__builtin_amdgcn_mbcnt_hi(~0u, __builtin_amdgcn_mbcnt_lo(~0u, z)); asm volatile("" : "+v"(t)); return t; }
; #define PG8_WAIT_V(n) asm volatile("s_waitcnt vmcnt(" #n ")" ::: "memory")
; #define PG8_WAIT_L(n) asm volatile("s_waitcnt lgkmcnt(" #n ")" ::: "memory")
; #define PG8_BAR __builtin_amdgcn_s_barrier()
; #define PG8_SCHED __builtin_amdgcn_sched_barrier(0)
; template <class Epi>
; __device__ __forceinline__ void gemm_phase(LAS unsigned char* lds, const Gemm g, const StaticOrder& S_in, const Epi& E, int sw) {
;     ...
;             PG8_BAR; PG8_WAIT_L(0); PG8_MMA(1, 0, At, B0); PG8_BAR; PG8_SCHED;
;             PG8_STAGE(PG8_SB(1, 1), b3 + hstepB, voffB);
;             PG8_WAIT_V(6); PG8_BAR; PG8_MMA(1, 1, At, B1); PG8_BAR;
;         }
;     EPI_ZERO_INIT
;     __device__ __forceinline__ void operator()(AccRef acc, const Unit& u, int sw) const {
;         const int tid_ = ltid(sw), lane_ = tid_ & 63, wr = sw >> 2, wc = sw & 3, fr = lane_ & 15, fq = lane_ >> 4;
;         const int row0 = u.pm * BM + wr * 64 + fr, c0 = u.pn * 128 + wc * 32 + 8 * fq;
; #pragma unroll
;         for (int ai = 0; ai < 2; ++ai)
; #pragma unroll
;             for (int m = 0; m < 4; ++m) { bf16_t* rowp = UG + (size_t)(row0 + ai * HALF + m * 16) * E + c0;
;                 float y[8];
; #pragma unroll
;                 for (int n = 0; n < 2; ++n)
; #pragma unroll
;                     for (int jp = 0; jp < 2; ++jp) {
;                         const f32x2 uu = (f32x2){acc[ai][0][m][n][2 * jp], acc[ai][0][m][n][2 * jp + 1]}, gg = (f32x2){acc[ai][1][m][n][2 * jp], acc[ai][1][m][n][2 * jp + 1]};
;                         const f32x2 za = (uu * uu * 0.044715f + 1.0f) * uu * (-1.44269504f * 1.59576912f), zg = gg * (-1.44269504f);
;                         f32x2 ea, eg; ea.x = __builtin_amdgcn_exp2f(za.x); ea.y = __builtin_amdgcn_exp2f(za.y); eg.x = __builtin_amdgcn_exp2f(zg.x); eg.y = __builtin_amdgcn_exp2f(zg.y);
;                         const f32x2 den = (ea + 1.0f) * (eg + 1.0f);
;                         f32x2 rc; rc.x = __builtin_amdgcn_rcpf(den.x); rc.y = __builtin_amdgcn_rcpf(den.y);
;                         const f32x2 yy = uu * gg * rc;
;                         y[4 * n + 2 * jp] = yy.x; y[4 * n + 2 * jp + 1] = yy.y; }
	s_waitcnt lgkmcnt(0)
	s_setprio 1
	s_waitcnt lgkmcnt(0)
	v_mfma_f32_16x16x32_bf16 v[62:65], v[144:147], v[160:163], v[62:65]
	v_mfma_f32_16x16x32_bf16 v[54:57], v[152:155], v[160:163], v[54:57]
	v_mfma_f32_16x16x32_bf16 v[46:49], v[144:147], v[172:175], v[46:49]
	v_mfma_f32_16x16x32_bf16 v[38:41], v[152:155], v[172:175], v[38:41]
	v_mfma_f32_16x16x32_bf16 v[30:33], v[144:147], v[180:183], v[30:33]
	v_mfma_f32_16x16x32_bf16 v[22:25], v[152:155], v[180:183], v[22:25]
	v_mfma_f32_16x16x32_bf16 v[14:17], v[144:147], v[188:191], v[14:17]
	v_mfma_f32_16x16x32_bf16 v[6:9], v[152:155], v[188:191], v[6:9]
	v_mfma_f32_16x16x32_bf16 v[62:65], v[148:151], v[164:167], v[62:65]
	v_mfma_f32_16x16x32_bf16 v[54:57], v[156:159], v[164:167], v[54:57]
	v_mfma_f32_16x16x32_bf16 v[46:49], v[148:151], v[176:179], v[46:49]
	v_mfma_f32_16x16x32_bf16 v[38:41], v[156:159], v[176:179], v[38:41]
	v_mfma_f32_16x16x32_bf16 v[30:33], v[148:151], v[184:187], v[30:33]
	v_mfma_f32_16x16x32_bf16 v[22:25], v[156:159], v[184:187], v[22:25]
	v_mfma_f32_16x16x32_bf16 v[14:17], v[148:151], v[192:195], v[14:17]
	v_mfma_f32_16x16x32_bf16 v[6:9], v[156:159], v[192:195], v[6:9]
	s_setprio 0
	s_barrier
	s_add_u32 s26, s26, 0x40080
	s_addc_u32 s27, s27, 0
	s_add_i32 s28, s28, s41
	v_lshl_add_u64 v[140:141], s[26:27], 0, v[0:1]
	s_mov_b32 m0, s28
	s_nop 0
	global_load_lds_dwordx4 v[140:141], off
	v_lshl_add_u64 v[140:141], s[26:27], 0, v[130:131]
	s_add_i32 m0, s28, 0x2000
	s_nop 0
	global_load_lds_dwordx4 v[140:141], off
	s_waitcnt vmcnt(6)
	s_barrier
	s_setprio 1
	v_mfma_f32_16x16x32_bf16 v[58:61], v[196:199], v[160:163], v[58:61]
	v_mfma_f32_16x16x32_bf16 v[50:53], v[204:207], v[160:163], v[50:53]
	v_mfma_f32_16x16x32_bf16 v[42:45], v[196:199], v[172:175], v[42:45]
	v_mfma_f32_16x16x32_bf16 v[34:37], v[204:207], v[172:175], v[34:37]
	v_mfma_f32_16x16x32_bf16 v[26:29], v[196:199], v[180:183], v[26:29]
	v_mfma_f32_16x16x32_bf16 v[18:21], v[204:207], v[180:183], v[18:21]
	v_mfma_f32_16x16x32_bf16 v[10:13], v[196:199], v[188:191], v[10:13]
	v_mfma_f32_16x16x32_bf16 v[2:5], v[204:207], v[188:191], v[2:5]
	v_mfma_f32_16x16x32_bf16 v[58:61], v[200:203], v[164:167], v[58:61]
	v_mfma_f32_16x16x32_bf16 v[50:53], v[208:211], v[164:167], v[50:53]
	v_mfma_f32_16x16x32_bf16 v[42:45], v[200:203], v[176:179], v[42:45]
	v_mfma_f32_16x16x32_bf16 v[34:37], v[208:211], v[176:179], v[34:37]
	v_mfma_f32_16x16x32_bf16 v[26:29], v[200:203], v[184:187], v[26:29]
	v_mfma_f32_16x16x32_bf16 v[18:21], v[208:211], v[184:187], v[18:21]
	v_mfma_f32_16x16x32_bf16 v[10:13], v[200:203], v[192:195], v[10:13]
	v_mfma_f32_16x16x32_bf16 v[2:5], v[208:211], v[192:195], v[2:5]
	s_setprio 0
	s_add_i32 s55, s55, 2
	s_add_u32 s24, s24, 0x100
	s_addc_u32 s25, s25, 0
	s_add_u32 s53, s53, 0x100
	s_addc_u32 s54, s54, 0
	s_cmp_gt_u32 s55, 13
	s_barrier
	s_cbranch_scc0 .LBB0_756
	s_mov_b32 s13, s75
	s_mov_b32 s17, s81
	v_pk_mul_f32 v[150:151], v[126:127], v[126:127]
	v_mbcnt_lo_u32_b32 v140, -1, s17
	v_mbcnt_hi_u32_b32 v140, -1, v140
	v_lshl_add_u32 v141, s13, 6, v140
	s_lshl_b32 s13, s22, 8
	s_mov_b32 s22, 0x3d372713
	v_pk_mul_f32 v[148:149], v[128:129], v[128:129]
	v_pk_fma_f32 v[150:151], v[150:151], s[22:23], 1.0 op_sel_hi:[1,0,0]
	v_pk_mul_f32 v[152:153], v[122:123], s[74:75] op_sel_hi:[1,0]
	v_pk_mul_f32 v[150:151], v[126:127], v[150:151]
	v_pk_mul_f32 v[122:123], v[126:127], v[122:123]
	v_pk_fma_f32 v[126:127], v[148:149], s[22:23], 1.0 op_sel_hi:[1,0,0]
	v_pk_mul_f32 v[148:149], v[124:125], s[74:75] op_sel_hi:[1,0]
	v_pk_mul_f32 v[126:127], v[128:129], v[126:127]
	v_exp_f32_e32 v148, v148
	v_pk_mul_f32 v[126:127], v[126:127], s[84:85] op_sel_hi:[1,0]
	v_exp_f32_e32 v149, v149
	v_exp_f32_e32 v126, v126
	v_exp_f32_e32 v127, v127
	v_pk_mul_f32 v[124:125], v[128:129], v[124:125]
	v_pk_mul_f32 v[128:129], v[118:119], v[118:119]
	v_pk_add_f32 v[148:149], v[148:149], 1.0 op_sel_hi:[1,0]
	v_pk_fma_f32 v[128:129], v[128:129], s[22:23], 1.0 op_sel_hi:[1,0,0]
	v_pk_add_f32 v[126:127], v[126:127], 1.0 op_sel_hi:[1,0]
	v_pk_mul_f32 v[128:129], v[118:119], v[128:129]
	v_pk_mul_f32 v[126:127], v[126:127], v[148:149]
	v_pk_mul_f32 v[128:129], v[128:129], s[84:85] op_sel_hi:[1,0]
	v_pk_mul_f32 v[148:149], v[114:115], s[74:75] op_sel_hi:[1,0]
	v_exp_f32_e32 v128, v128
	v_exp_f32_e32 v129, v129
	v_exp_f32_e32 v148, v148
	v_exp_f32_e32 v149, v149
	v_rcp_f32_e32 v126, v126
	v_pk_add_f32 v[128:129], v[128:129], 1.0 op_sel_hi:[1,0]
	v_rcp_f32_e32 v127, v127
	v_pk_add_f32 v[148:149], v[148:149], 1.0 op_sel_hi:[1,0]
	v_pk_mul_f32 v[114:115], v[118:119], v[114:115]
	v_pk_mul_f32 v[128:129], v[128:129], v[148:149]
	v_pk_mul_f32 v[124:125], v[124:125], v[126:127]
	v_rcp_f32_e32 v128, v128
	v_rcp_f32_e32 v129, v129
	v_pk_mul_f32 v[126:127], v[120:121], v[120:121]
	v_pk_mul_f32 v[150:151], v[150:151], s[84:85] op_sel_hi:[1,0]
	v_pk_mul_f32 v[118:119], v[116:117], s[74:75] op_sel_hi:[1,0]
	v_pk_mul_f32 v[128:129], v[114:115], v[128:129]
	v_pk_fma_f32 v[114:115], v[126:127], s[22:23], 1.0 op_sel_hi:[1,0,0]
	v_exp_f32_e32 v150, v150
	v_pk_mul_f32 v[114:115], v[120:121], v[114:115]
	v_exp_f32_e32 v151, v151
	v_pk_mul_f32 v[114:115], v[114:115], s[84:85] op_sel_hi:[1,0]
	v_exp_f32_e32 v152, v152
	v_exp_f32_e32 v153, v153
	v_exp_f32_e32 v114, v114
	v_exp_f32_e32 v115, v115
	v_exp_f32_e32 v118, v118
	v_exp_f32_e32 v119, v119
	v_pk_add_f32 v[150:151], v[150:151], 1.0 op_sel_hi:[1,0]
	v_pk_add_f32 v[152:153], v[152:153], 1.0 op_sel_hi:[1,0]
	v_pk_add_f32 v[114:115], v[114:115], 1.0 op_sel_hi:[1,0]
	v_pk_add_f32 v[118:119], v[118:119], 1.0 op_sel_hi:[1,0]
	v_mov_b32_e32 v140, s13
	v_and_b32_e32 v141, 63, v141
	v_pk_mul_f32 v[150:151], v[150:151], v[152:153]
; __device__ __forceinline__ unsigned cvt_pk_bf16(float lo, float hi) { unsigned r; asm volatile("v_cvt_pk_bf16_f32 %0, %1, %2" : "=v"(r) : "v"(lo), "v"(hi)); return r; }
;     EPI_ZERO_INIT
;     __device__ __forceinline__ void operator()(AccRef acc, const Unit& u, int sw) const {
;     ...
; #pragma unroll
;         for (int ai = 0; ai < 2; ++ai)
; #pragma unroll
;             for (int m = 0; m < 4; ++m) { bf16_t* rowp = UG + (size_t)(row0 + ai * HALF + m * 16) * E + c0;
;                 float y[8];
; #pragma unroll
;                 for (int n = 0; n < 2; ++n)
; #pragma unroll
;                     for (int jp = 0; jp < 2; ++jp) {
;                         const f32x2 uu = (f32x2){acc[ai][0][m][n][2 * jp], acc[ai][0][m][n][2 * jp + 1]}, gg = (f32x2){acc[ai][1][m][n][2 * jp], acc[ai][1][m][n][2 * jp + 1]};
;                         const f32x2 za = (uu * uu * 0.044715f + 1.0f) * uu * (-1.44269504f * 1.59576912f), zg = gg * (-1.44269504f);
;                         f32x2 ea, eg; ea.x = __builtin_amdgcn_exp2f(za.x); ea.y = __builtin_amdgcn_exp2f(za.y); eg.x = __builtin_amdgcn_exp2f(zg.x); eg.y = __builtin_amdgcn_exp2f(zg.y);
;                         const f32x2 den = (ea + 1.0f) * (eg + 1.0f);
;                         f32x2 rc; rc.x = __builtin_amdgcn_rcpf(den.x); rc.y = __builtin_amdgcn_rcpf(den.y);
;                         const f32x2 yy = uu * gg * rc;
;                         y[4 * n + 2 * jp] = yy.x; y[4 * n + 2 * jp + 1] = yy.y; }
;                 u32x4 w; w.x = cvt_pk_bf16(y[0], y[1]); w.y = cvt_pk_bf16(y[2], y[3]); w.z = cvt_pk_bf16(y[4], y[5]); w.w = cvt_pk_bf16(y[6], y[7]);
;                 *(u32x4*)rowp = w; }
	v_pk_mul_f32 v[114:115], v[114:115], v[118:119]
	v_lshlrev_b32_e32 v141, 3, v141
	v_rcp_f32_e32 v150, v150
	v_rcp_f32_e32 v151, v151
	v_rcp_f32_e32 v114, v114
	v_rcp_f32_e32 v115, v115
	v_lshl_or_b32 v141, s50, 14, v141
	v_lshl_or_b32 v144, s85, 7, v141
	v_lshl_or_b32 v144, s3, 5, v144
	v_ashrrev_i32_e32 v141, 31, v140
	v_ashrrev_i32_e32 v145, 31, v144
	v_lshlrev_b64 v[146:147], 12, v[140:141]
	v_pk_mul_f32 v[116:117], v[120:121], v[116:117]
	v_lshl_add_u64 v[146:147], s[10:11], 0, v[146:147]
	v_pk_mul_f32 v[122:123], v[122:123], v[150:151]
	v_pk_mul_f32 v[126:127], v[116:117], v[114:115]
	v_lshlrev_b64 v[116:117], 1, v[144:145]
	v_lshl_add_u64 v[114:115], v[146:147], 0, v[116:117]
	v_cvt_pk_bf16_f32 v118, v122, v123
	v_cvt_pk_bf16_f32 v119, v124, v125
	v_cvt_pk_bf16_f32 v120, v128, v129
	v_cvt_pk_bf16_f32 v121, v126, v127
	v_pk_mul_f32 v[122:123], v[110:111], v[110:111]
	global_store_dwordx4 v[114:115], v[118:121], off nt
	v_pk_fma_f32 v[122:123], v[122:123], s[22:23], 1.0 op_sel_hi:[1,0,0]
	v_pk_mul_f32 v[124:125], v[106:107], s[74:75] op_sel_hi:[1,0]
	v_pk_mul_f32 v[120:121], v[112:113], v[112:113]
	v_pk_mul_f32 v[122:123], v[110:111], v[122:123]
	v_pk_mul_f32 v[106:107], v[110:111], v[106:107]
	v_pk_fma_f32 v[110:111], v[120:121], s[22:23], 1.0 op_sel_hi:[1,0,0]
	v_pk_mul_f32 v[120:121], v[108:109], s[74:75] op_sel_hi:[1,0]
	v_pk_mul_f32 v[110:111], v[112:113], v[110:111]
	v_exp_f32_e32 v120, v120
	v_pk_mul_f32 v[110:111], v[110:111], s[84:85] op_sel_hi:[1,0]
	v_exp_f32_e32 v121, v121
	v_exp_f32_e32 v110, v110
	v_exp_f32_e32 v111, v111
	v_pk_mul_f32 v[108:109], v[112:113], v[108:109]
	v_pk_mul_f32 v[112:113], v[102:103], v[102:103]
	v_pk_add_f32 v[120:121], v[120:121], 1.0 op_sel_hi:[1,0]
	v_pk_fma_f32 v[112:113], v[112:113], s[22:23], 1.0 op_sel_hi:[1,0,0]
	v_pk_add_f32 v[110:111], v[110:111], 1.0 op_sel_hi:[1,0]
	v_pk_mul_f32 v[112:113], v[102:103], v[112:113]
	v_pk_mul_f32 v[110:111], v[110:111], v[120:121]
	v_pk_mul_f32 v[112:113], v[112:113], s[84:85] op_sel_hi:[1,0]
	v_pk_mul_f32 v[120:121], v[98:99], s[74:75] op_sel_hi:[1,0]
	v_exp_f32_e32 v112, v112
	v_exp_f32_e32 v113, v113
	v_exp_f32_e32 v120, v120
	v_exp_f32_e32 v121, v121
	v_rcp_f32_e32 v110, v110
	v_pk_add_f32 v[112:113], v[112:113], 1.0 op_sel_hi:[1,0]
	v_rcp_f32_e32 v111, v111
	v_pk_add_f32 v[120:121], v[120:121], 1.0 op_sel_hi:[1,0]
	v_pk_mul_f32 v[98:99], v[102:103], v[98:99]
	v_pk_mul_f32 v[112:113], v[112:113], v[120:121]
	v_pk_mul_f32 v[108:109], v[108:109], v[110:111]
	v_rcp_f32_e32 v112, v112
	v_rcp_f32_e32 v113, v113
	v_pk_mul_f32 v[110:111], v[104:105], v[104:105]
	v_pk_mul_f32 v[122:123], v[122:123], s[84:85] op_sel_hi:[1,0]
	v_exp_f32_e32 v124, v124
	v_pk_mul_f32 v[102:103], v[98:99], v[112:113]
	v_pk_fma_f32 v[98:99], v[110:111], s[22:23], 1.0 op_sel_hi:[1,0,0]
	v_pk_mul_f32 v[110:111], v[100:101], s[74:75] op_sel_hi:[1,0]
	v_pk_mul_f32 v[98:99], v[104:105], v[98:99]
	v_exp_f32_e32 v122, v122
	v_pk_mul_f32 v[98:99], v[98:99], s[84:85] op_sel_hi:[1,0]
	v_exp_f32_e32 v123, v123
	v_exp_f32_e32 v125, v125
	v_exp_f32_e32 v98, v98
	v_exp_f32_e32 v99, v99
	v_exp_f32_e32 v110, v110
	v_exp_f32_e32 v111, v111
	v_pk_add_f32 v[122:123], v[122:123], 1.0 op_sel_hi:[1,0]
	v_pk_add_f32 v[124:125], v[124:125], 1.0 op_sel_hi:[1,0]
	v_pk_add_f32 v[98:99], v[98:99], 1.0 op_sel_hi:[1,0]
	v_pk_add_f32 v[110:111], v[110:111], 1.0 op_sel_hi:[1,0]
	v_pk_mul_f32 v[122:123], v[122:123], v[124:125]
	v_pk_mul_f32 v[98:99], v[98:99], v[110:111]
	v_or_b32_e32 v118, 16, v140
	v_rcp_f32_e32 v122, v122
	v_rcp_f32_e32 v123, v123
	v_rcp_f32_e32 v98, v98
	v_rcp_f32_e32 v99, v99
	v_ashrrev_i32_e32 v119, 31, v118
	v_lshlrev_b64 v[118:119], 12, v[118:119]
	v_lshl_add_u64 v[118:119], s[10:11], 0, v[118:119]
	v_pk_mul_f32 v[100:101], v[104:105], v[100:101]
	v_pk_mul_f32 v[106:107], v[106:107], v[122:123]
	v_pk_mul_f32 v[104:105], v[100:101], v[98:99]
	v_lshl_add_u64 v[110:111], v[118:119], 0, v[116:117]
	v_cvt_pk_bf16_f32 v98, v106, v107
	v_cvt_pk_bf16_f32 v99, v108, v109
	v_cvt_pk_bf16_f32 v100, v102, v103
	v_cvt_pk_bf16_f32 v101, v104, v105
	v_pk_mul_f32 v[102:103], v[94:95], v[94:95]
	global_store_dwordx4 v[114:115], v[98:101], off offset:1024 nt
	v_pk_fma_f32 v[102:103], v[102:103], s[22:23], 1.0 op_sel_hi:[1,0,0]
	v_pk_mul_f32 v[104:105], v[90:91], s[74:75] op_sel_hi:[1,0]
	v_pk_mul_f32 v[100:101], v[96:97], v[96:97]
	v_pk_mul_f32 v[102:103], v[94:95], v[102:103]
	v_pk_mul_f32 v[90:91], v[94:95], v[90:91]
	v_pk_fma_f32 v[94:95], v[100:101], s[22:23], 1.0 op_sel_hi:[1,0,0]
	v_pk_mul_f32 v[100:101], v[92:93], s[74:75] op_sel_hi:[1,0]
	v_pk_mul_f32 v[94:95], v[96:97], v[94:95]
	v_exp_f32_e32 v100, v100
	v_pk_mul_f32 v[94:95], v[94:95], s[84:85] op_sel_hi:[1,0]
	v_exp_f32_e32 v101, v101
	v_exp_f32_e32 v94, v94
	v_exp_f32_e32 v95, v95
	v_pk_mul_f32 v[92:93], v[96:97], v[92:93]
	v_pk_mul_f32 v[96:97], v[86:87], v[86:87]
	v_pk_add_f32 v[100:101], v[100:101], 1.0 op_sel_hi:[1,0]
	v_pk_fma_f32 v[96:97], v[96:97], s[22:23], 1.0 op_sel_hi:[1,0,0]
	v_pk_add_f32 v[94:95], v[94:95], 1.0 op_sel_hi:[1,0]
	v_pk_mul_f32 v[96:97], v[86:87], v[96:97]
	v_pk_mul_f32 v[94:95], v[94:95], v[100:101]
	v_pk_mul_f32 v[96:97], v[96:97], s[84:85] op_sel_hi:[1,0]
	v_pk_mul_f32 v[100:101], v[82:83], s[74:75] op_sel_hi:[1,0]
	v_exp_f32_e32 v96, v96
	v_exp_f32_e32 v97, v97
	v_exp_f32_e32 v100, v100
	v_exp_f32_e32 v101, v101
	v_rcp_f32_e32 v94, v94
	v_pk_add_f32 v[96:97], v[96:97], 1.0 op_sel_hi:[1,0]
	v_rcp_f32_e32 v95, v95
	v_pk_add_f32 v[100:101], v[100:101], 1.0 op_sel_hi:[1,0]
	v_pk_mul_f32 v[82:83], v[86:87], v[82:83]
	v_pk_mul_f32 v[96:97], v[96:97], v[100:101]
	v_pk_mul_f32 v[92:93], v[92:93], v[94:95]
	v_rcp_f32_e32 v96, v96
; __device__ __forceinline__ unsigned cvt_pk_bf16(float lo, float hi) { unsigned r; asm volatile("v_cvt_pk_bf16_f32 %0, %1, %2" : "=v"(r) : "v"(lo), "v"(hi)); return r; }
;     EPI_ZERO_INIT
;     __device__ __forceinline__ void operator()(AccRef acc, const Unit& u, int sw) const {
;     ...
; #pragma unroll
;         for (int ai = 0; ai < 2; ++ai)
; #pragma unroll
;             for (int m = 0; m < 4; ++m) { bf16_t* rowp = UG + (size_t)(row0 + ai * HALF + m * 16) * E + c0;
;                 float y[8];
; #pragma unroll
;                 for (int n = 0; n < 2; ++n)
; #pragma unroll
;                     for (int jp = 0; jp < 2; ++jp) {
;                         const f32x2 uu = (f32x2){acc[ai][0][m][n][2 * jp], acc[ai][0][m][n][2 * jp + 1]}, gg = (f32x2){acc[ai][1][m][n][2 * jp], acc[ai][1][m][n][2 * jp + 1]};
;                         const f32x2 za = (uu * uu * 0.044715f + 1.0f) * uu * (-1.44269504f * 1.59576912f), zg = gg * (-1.44269504f);
;                         f32x2 ea, eg; ea.x = __builtin_amdgcn_exp2f(za.x); ea.y = __builtin_amdgcn_exp2f(za.y); eg.x = __builtin_amdgcn_exp2f(zg.x); eg.y = __builtin_amdgcn_exp2f(zg.y);
;                         const f32x2 den = (ea + 1.0f) * (eg + 1.0f);
;                         f32x2 rc; rc.x = __builtin_amdgcn_rcpf(den.x); rc.y = __builtin_amdgcn_rcpf(den.y);
;                         const f32x2 yy = uu * gg * rc;
;                         y[4 * n + 2 * jp] = yy.x; y[4 * n + 2 * jp + 1] = yy.y; }
;                 u32x4 w; w.x = cvt_pk_bf16(y[0], y[1]); w.y = cvt_pk_bf16(y[2], y[3]); w.z = cvt_pk_bf16(y[4], y[5]); w.w = cvt_pk_bf16(y[6], y[7]);
;                 *(u32x4*)rowp = w; }
	v_rcp_f32_e32 v97, v97
	v_pk_mul_f32 v[94:95], v[88:89], v[88:89]
	v_pk_mul_f32 v[102:103], v[102:103], s[84:85] op_sel_hi:[1,0]
	v_exp_f32_e32 v104, v104
	v_pk_mul_f32 v[86:87], v[82:83], v[96:97]
	v_pk_fma_f32 v[82:83], v[94:95], s[22:23], 1.0 op_sel_hi:[1,0,0]
	v_pk_mul_f32 v[94:95], v[84:85], s[74:75] op_sel_hi:[1,0]
	v_pk_mul_f32 v[82:83], v[88:89], v[82:83]
	v_exp_f32_e32 v102, v102
	v_pk_mul_f32 v[82:83], v[82:83], s[84:85] op_sel_hi:[1,0]
	v_exp_f32_e32 v103, v103
	v_exp_f32_e32 v105, v105
	v_exp_f32_e32 v82, v82
	v_exp_f32_e32 v83, v83
	v_exp_f32_e32 v94, v94
	v_exp_f32_e32 v95, v95
	v_pk_add_f32 v[102:103], v[102:103], 1.0 op_sel_hi:[1,0]
	v_pk_add_f32 v[104:105], v[104:105], 1.0 op_sel_hi:[1,0]
	v_pk_add_f32 v[82:83], v[82:83], 1.0 op_sel_hi:[1,0]
	v_pk_add_f32 v[94:95], v[94:95], 1.0 op_sel_hi:[1,0]
	v_pk_mul_f32 v[102:103], v[102:103], v[104:105]
	v_pk_mul_f32 v[82:83], v[82:83], v[94:95]
	v_or_b32_e32 v98, 32, v140
	v_rcp_f32_e32 v102, v102
	v_rcp_f32_e32 v103, v103
	v_rcp_f32_e32 v82, v82
	v_rcp_f32_e32 v83, v83
	v_ashrrev_i32_e32 v99, 31, v98
	v_lshlrev_b64 v[98:99], 12, v[98:99]
	v_lshl_add_u64 v[98:99], s[10:11], 0, v[98:99]
	v_pk_mul_f32 v[84:85], v[88:89], v[84:85]
	v_pk_mul_f32 v[90:91], v[90:91], v[102:103]
	v_pk_mul_f32 v[88:89], v[84:85], v[82:83]
	v_lshl_add_u64 v[94:95], v[98:99], 0, v[116:117]
	v_cvt_pk_bf16_f32 v82, v90, v91
	v_cvt_pk_bf16_f32 v83, v92, v93
	v_cvt_pk_bf16_f32 v84, v86, v87
	v_cvt_pk_bf16_f32 v85, v88, v89
	v_pk_mul_f32 v[86:87], v[78:79], v[78:79]
	global_store_dwordx4 v[114:115], v[82:85], off offset:2048 nt
	v_pk_fma_f32 v[86:87], v[86:87], s[22:23], 1.0 op_sel_hi:[1,0,0]
	v_pk_mul_f32 v[88:89], v[74:75], s[74:75] op_sel_hi:[1,0]
	v_pk_mul_f32 v[84:85], v[80:81], v[80:81]
	v_pk_mul_f32 v[86:87], v[78:79], v[86:87]
	v_pk_mul_f32 v[74:75], v[78:79], v[74:75]
	v_pk_fma_f32 v[78:79], v[84:85], s[22:23], 1.0 op_sel_hi:[1,0,0]
	v_pk_mul_f32 v[84:85], v[76:77], s[74:75] op_sel_hi:[1,0]
	v_pk_mul_f32 v[78:79], v[80:81], v[78:79]
	v_exp_f32_e32 v84, v84
	v_pk_mul_f32 v[78:79], v[78:79], s[84:85] op_sel_hi:[1,0]
	v_exp_f32_e32 v85, v85
	v_exp_f32_e32 v78, v78
	v_exp_f32_e32 v79, v79
	v_pk_mul_f32 v[76:77], v[80:81], v[76:77]
	v_pk_mul_f32 v[80:81], v[70:71], v[70:71]
	v_pk_add_f32 v[84:85], v[84:85], 1.0 op_sel_hi:[1,0]
	v_pk_fma_f32 v[80:81], v[80:81], s[22:23], 1.0 op_sel_hi:[1,0,0]
	v_pk_add_f32 v[78:79], v[78:79], 1.0 op_sel_hi:[1,0]
	v_pk_mul_f32 v[80:81], v[70:71], v[80:81]
	v_pk_mul_f32 v[78:79], v[78:79], v[84:85]
	v_pk_mul_f32 v[80:81], v[80:81], s[84:85] op_sel_hi:[1,0]
	v_pk_mul_f32 v[84:85], v[66:67], s[74:75] op_sel_hi:[1,0]
	v_exp_f32_e32 v80, v80
	v_exp_f32_e32 v81, v81
	v_exp_f32_e32 v84, v84
	v_exp_f32_e32 v85, v85
	v_rcp_f32_e32 v78, v78
	v_pk_add_f32 v[80:81], v[80:81], 1.0 op_sel_hi:[1,0]
	v_rcp_f32_e32 v79, v79
	v_pk_add_f32 v[84:85], v[84:85], 1.0 op_sel_hi:[1,0]
	v_pk_mul_f32 v[66:67], v[70:71], v[66:67]
	v_pk_mul_f32 v[80:81], v[80:81], v[84:85]
	v_pk_mul_f32 v[76:77], v[76:77], v[78:79]
	v_rcp_f32_e32 v80, v80
	v_rcp_f32_e32 v81, v81
	v_pk_mul_f32 v[78:79], v[72:73], v[72:73]
	v_pk_mul_f32 v[86:87], v[86:87], s[84:85] op_sel_hi:[1,0]
	v_exp_f32_e32 v88, v88
	v_pk_mul_f32 v[70:71], v[66:67], v[80:81]
	v_pk_fma_f32 v[66:67], v[78:79], s[22:23], 1.0 op_sel_hi:[1,0,0]
	v_pk_mul_f32 v[78:79], v[68:69], s[74:75] op_sel_hi:[1,0]
	v_pk_mul_f32 v[66:67], v[72:73], v[66:67]
	v_exp_f32_e32 v86, v86
	v_pk_mul_f32 v[66:67], v[66:67], s[84:85] op_sel_hi:[1,0]
	v_exp_f32_e32 v87, v87
	v_exp_f32_e32 v89, v89
	v_exp_f32_e32 v66, v66
	v_exp_f32_e32 v67, v67
	v_exp_f32_e32 v78, v78
	v_exp_f32_e32 v79, v79
	v_pk_add_f32 v[86:87], v[86:87], 1.0 op_sel_hi:[1,0]
	v_pk_add_f32 v[88:89], v[88:89], 1.0 op_sel_hi:[1,0]
	v_pk_add_f32 v[66:67], v[66:67], 1.0 op_sel_hi:[1,0]
	v_pk_add_f32 v[78:79], v[78:79], 1.0 op_sel_hi:[1,0]
	v_pk_mul_f32 v[86:87], v[86:87], v[88:89]
	v_pk_mul_f32 v[66:67], v[66:67], v[78:79]
	v_or_b32_e32 v82, 48, v140
	v_rcp_f32_e32 v86, v86
	v_rcp_f32_e32 v87, v87
	v_rcp_f32_e32 v66, v66
	v_rcp_f32_e32 v67, v67
	v_ashrrev_i32_e32 v83, 31, v82
	v_lshlrev_b64 v[82:83], 12, v[82:83]
	v_lshl_add_u64 v[82:83], s[10:11], 0, v[82:83]
	v_pk_mul_f32 v[68:69], v[72:73], v[68:69]
	v_pk_mul_f32 v[74:75], v[74:75], v[86:87]
	v_pk_mul_f32 v[72:73], v[68:69], v[66:67]
	v_lshl_add_u64 v[78:79], v[82:83], 0, v[116:117]
	v_cvt_pk_bf16_f32 v66, v74, v75
	v_cvt_pk_bf16_f32 v67, v76, v77
	v_cvt_pk_bf16_f32 v68, v70, v71
	v_cvt_pk_bf16_f32 v69, v72, v73
	global_store_dwordx4 v[114:115], v[66:69], off offset:3072 nt
	v_pk_mul_f32 v[70:71], v[58:59], s[74:75] op_sel_hi:[1,0]
	v_pk_mul_f32 v[58:59], v[62:63], v[58:59]
	v_pk_mul_f32 v[68:69], v[62:63], v[62:63]
	v_pk_mul_f32 v[66:67], v[64:65], v[64:65]
	v_pk_fma_f32 v[68:69], v[68:69], s[22:23], 1.0 op_sel_hi:[1,0,0]
	v_exp_f32_e32 v70, v70
	v_pk_mul_f32 v[68:69], v[62:63], v[68:69]
	v_pk_fma_f32 v[62:63], v[66:67], s[22:23], 1.0 op_sel_hi:[1,0,0]
	v_pk_mul_f32 v[66:67], v[60:61], s[74:75] op_sel_hi:[1,0]
	v_pk_mul_f32 v[62:63], v[64:65], v[62:63]
	v_exp_f32_e32 v66, v66
	v_pk_mul_f32 v[62:63], v[62:63], s[84:85] op_sel_hi:[1,0]
	v_exp_f32_e32 v67, v67
	v_exp_f32_e32 v62, v62
	v_exp_f32_e32 v63, v63
	v_pk_mul_f32 v[60:61], v[64:65], v[60:61]
	v_pk_mul_f32 v[64:65], v[54:55], v[54:55]
	v_pk_add_f32 v[66:67], v[66:67], 1.0 op_sel_hi:[1,0]
	v_pk_fma_f32 v[64:65], v[64:65], s[22:23], 1.0 op_sel_hi:[1,0,0]
	v_pk_add_f32 v[62:63], v[62:63], 1.0 op_sel_hi:[1,0]
	v_pk_mul_f32 v[64:65], v[54:55], v[64:65]
	v_pk_mul_f32 v[62:63], v[62:63], v[66:67]
	v_pk_mul_f32 v[64:65], v[64:65], s[84:85] op_sel_hi:[1,0]
	v_pk_mul_f32 v[66:67], v[50:51], s[74:75] op_sel_hi:[1,0]
; __device__ __forceinline__ unsigned cvt_pk_bf16(float lo, float hi) { unsigned r; asm volatile("v_cvt_pk_bf16_f32 %0, %1, %2" : "=v"(r) : "v"(lo), "v"(hi)); return r; }
;     EPI_ZERO_INIT
;     __device__ __forceinline__ void operator()(AccRef acc, const Unit& u, int sw) const {
;     ...
; #pragma unroll
;         for (int ai = 0; ai < 2; ++ai)
; #pragma unroll
;             for (int m = 0; m < 4; ++m) { bf16_t* rowp = UG + (size_t)(row0 + ai * HALF + m * 16) * E + c0;
;                 float y[8];
; #pragma unroll
;                 for (int n = 0; n < 2; ++n)
; #pragma unroll
;                     for (int jp = 0; jp < 2; ++jp) {
;                         const f32x2 uu = (f32x2){acc[ai][0][m][n][2 * jp], acc[ai][0][m][n][2 * jp + 1]}, gg = (f32x2){acc[ai][1][m][n][2 * jp], acc[ai][1][m][n][2 * jp + 1]};
;                         const f32x2 za = (uu * uu * 0.044715f + 1.0f) * uu * (-1.44269504f * 1.59576912f), zg = gg * (-1.44269504f);
;                         f32x2 ea, eg; ea.x = __builtin_amdgcn_exp2f(za.x); ea.y = __builtin_amdgcn_exp2f(za.y); eg.x = __builtin_amdgcn_exp2f(zg.x); eg.y = __builtin_amdgcn_exp2f(zg.y);
;                         const f32x2 den = (ea + 1.0f) * (eg + 1.0f);
;                         f32x2 rc; rc.x = __builtin_amdgcn_rcpf(den.x); rc.y = __builtin_amdgcn_rcpf(den.y);
;                         const f32x2 yy = uu * gg * rc;
;                         y[4 * n + 2 * jp] = yy.x; y[4 * n + 2 * jp + 1] = yy.y; }
;                 u32x4 w; w.x = cvt_pk_bf16(y[0], y[1]); w.y = cvt_pk_bf16(y[2], y[3]); w.z = cvt_pk_bf16(y[4], y[5]); w.w = cvt_pk_bf16(y[6], y[7]);
;                 *(u32x4*)rowp = w; }
	v_exp_f32_e32 v64, v64
	v_exp_f32_e32 v65, v65
	v_exp_f32_e32 v66, v66
	v_exp_f32_e32 v67, v67
	v_rcp_f32_e32 v62, v62
	v_pk_add_f32 v[64:65], v[64:65], 1.0 op_sel_hi:[1,0]
	v_rcp_f32_e32 v63, v63
	v_pk_add_f32 v[66:67], v[66:67], 1.0 op_sel_hi:[1,0]
	v_pk_mul_f32 v[50:51], v[54:55], v[50:51]
	v_pk_mul_f32 v[64:65], v[64:65], v[66:67]
	v_pk_mul_f32 v[60:61], v[60:61], v[62:63]
	v_rcp_f32_e32 v64, v64
	v_rcp_f32_e32 v65, v65
	v_pk_mul_f32 v[62:63], v[56:57], v[56:57]
	v_pk_mul_f32 v[68:69], v[68:69], s[84:85] op_sel_hi:[1,0]
	v_exp_f32_e32 v71, v71
	v_pk_mul_f32 v[54:55], v[50:51], v[64:65]
	v_pk_fma_f32 v[50:51], v[62:63], s[22:23], 1.0 op_sel_hi:[1,0,0]
	v_pk_mul_f32 v[62:63], v[52:53], s[74:75] op_sel_hi:[1,0]
	v_pk_mul_f32 v[50:51], v[56:57], v[50:51]
	v_exp_f32_e32 v68, v68
	v_pk_mul_f32 v[50:51], v[50:51], s[84:85] op_sel_hi:[1,0]
	v_exp_f32_e32 v69, v69
	v_exp_f32_e32 v50, v50
	v_exp_f32_e32 v51, v51
	v_exp_f32_e32 v62, v62
	v_exp_f32_e32 v63, v63
	v_pk_add_f32 v[68:69], v[68:69], 1.0 op_sel_hi:[1,0]
	v_pk_add_f32 v[70:71], v[70:71], 1.0 op_sel_hi:[1,0]
	v_pk_add_f32 v[50:51], v[50:51], 1.0 op_sel_hi:[1,0]
	v_pk_add_f32 v[62:63], v[62:63], 1.0 op_sel_hi:[1,0]
	v_pk_mul_f32 v[68:69], v[68:69], v[70:71]
	v_pk_mul_f32 v[50:51], v[50:51], v[62:63]
	v_rcp_f32_e32 v68, v68
	v_rcp_f32_e32 v69, v69
	v_rcp_f32_e32 v50, v50
	v_rcp_f32_e32 v51, v51
	v_pk_mul_f32 v[52:53], v[56:57], v[52:53]
	s_mov_b32 s13, 0x80000
	v_pk_mul_f32 v[58:59], v[58:59], v[68:69]
	v_pk_mul_f32 v[56:57], v[52:53], v[50:51]
	v_cvt_pk_bf16_f32 v50, v58, v59
	v_cvt_pk_bf16_f32 v51, v60, v61
	v_cvt_pk_bf16_f32 v52, v54, v55
	v_add_co_u32_e32 v54, vcc, s13, v114
	v_cvt_pk_bf16_f32 v53, v56, v57
	s_mov_b32 s13, 0x80400
	s_nop 0
	v_addc_co_u32_e32 v55, vcc, 0, v115, vcc
	global_store_dwordx4 v[54:55], v[50:53], off nt
	v_pk_mul_f32 v[54:55], v[42:43], s[74:75] op_sel_hi:[1,0]
	v_pk_mul_f32 v[42:43], v[46:47], v[42:43]
	v_pk_mul_f32 v[52:53], v[46:47], v[46:47]
	v_pk_mul_f32 v[50:51], v[48:49], v[48:49]
	v_pk_fma_f32 v[52:53], v[52:53], s[22:23], 1.0 op_sel_hi:[1,0,0]
	v_exp_f32_e32 v54, v54
	v_pk_mul_f32 v[52:53], v[46:47], v[52:53]
	v_pk_fma_f32 v[46:47], v[50:51], s[22:23], 1.0 op_sel_hi:[1,0,0]
	v_pk_mul_f32 v[50:51], v[44:45], s[74:75] op_sel_hi:[1,0]
	v_pk_mul_f32 v[46:47], v[48:49], v[46:47]
	v_exp_f32_e32 v50, v50
	v_pk_mul_f32 v[46:47], v[46:47], s[84:85] op_sel_hi:[1,0]
	v_exp_f32_e32 v51, v51
	v_exp_f32_e32 v46, v46
	v_exp_f32_e32 v47, v47
	v_pk_mul_f32 v[44:45], v[48:49], v[44:45]
	v_pk_mul_f32 v[48:49], v[38:39], v[38:39]
	v_pk_add_f32 v[50:51], v[50:51], 1.0 op_sel_hi:[1,0]
	v_pk_fma_f32 v[48:49], v[48:49], s[22:23], 1.0 op_sel_hi:[1,0,0]
	v_pk_add_f32 v[46:47], v[46:47], 1.0 op_sel_hi:[1,0]
	v_pk_mul_f32 v[48:49], v[38:39], v[48:49]
	v_pk_mul_f32 v[46:47], v[46:47], v[50:51]
	v_pk_mul_f32 v[48:49], v[48:49], s[84:85] op_sel_hi:[1,0]
	v_pk_mul_f32 v[50:51], v[34:35], s[74:75] op_sel_hi:[1,0]
	v_exp_f32_e32 v48, v48
	v_exp_f32_e32 v49, v49
	v_exp_f32_e32 v50, v50
	v_exp_f32_e32 v51, v51
	v_rcp_f32_e32 v46, v46
	v_pk_add_f32 v[48:49], v[48:49], 1.0 op_sel_hi:[1,0]
	v_rcp_f32_e32 v47, v47
	v_pk_add_f32 v[50:51], v[50:51], 1.0 op_sel_hi:[1,0]
	v_pk_mul_f32 v[34:35], v[38:39], v[34:35]
	v_pk_mul_f32 v[48:49], v[48:49], v[50:51]
	v_pk_mul_f32 v[44:45], v[44:45], v[46:47]
	v_rcp_f32_e32 v48, v48
	v_rcp_f32_e32 v49, v49
	v_pk_mul_f32 v[46:47], v[40:41], v[40:41]
	v_pk_mul_f32 v[52:53], v[52:53], s[84:85] op_sel_hi:[1,0]
	v_exp_f32_e32 v55, v55
	v_pk_mul_f32 v[38:39], v[34:35], v[48:49]
	v_pk_fma_f32 v[34:35], v[46:47], s[22:23], 1.0 op_sel_hi:[1,0,0]
	v_pk_mul_f32 v[46:47], v[36:37], s[74:75] op_sel_hi:[1,0]
	v_pk_mul_f32 v[34:35], v[40:41], v[34:35]
	v_exp_f32_e32 v52, v52
	v_pk_mul_f32 v[34:35], v[34:35], s[84:85] op_sel_hi:[1,0]
	v_exp_f32_e32 v53, v53
	v_exp_f32_e32 v34, v34
	v_exp_f32_e32 v35, v35
	v_exp_f32_e32 v46, v46
	v_exp_f32_e32 v47, v47
	v_pk_add_f32 v[52:53], v[52:53], 1.0 op_sel_hi:[1,0]
	v_pk_add_f32 v[54:55], v[54:55], 1.0 op_sel_hi:[1,0]
	v_pk_add_f32 v[34:35], v[34:35], 1.0 op_sel_hi:[1,0]
	v_pk_add_f32 v[46:47], v[46:47], 1.0 op_sel_hi:[1,0]
	v_pk_mul_f32 v[52:53], v[52:53], v[54:55]
	v_pk_mul_f32 v[34:35], v[34:35], v[46:47]
	v_rcp_f32_e32 v52, v52
	v_rcp_f32_e32 v53, v53
	v_rcp_f32_e32 v34, v34
	v_rcp_f32_e32 v35, v35
	v_pk_mul_f32 v[36:37], v[40:41], v[36:37]
	v_pk_mul_f32 v[42:43], v[42:43], v[52:53]
	v_pk_mul_f32 v[40:41], v[36:37], v[34:35]
	v_cvt_pk_bf16_f32 v34, v42, v43
	v_cvt_pk_bf16_f32 v35, v44, v45
	v_cvt_pk_bf16_f32 v36, v38, v39
	v_add_co_u32_e32 v38, vcc, s13, v114
	v_cvt_pk_bf16_f32 v37, v40, v41
	s_mov_b32 s13, 0x80800
	s_nop 0
	v_addc_co_u32_e32 v39, vcc, 0, v115, vcc
	global_store_dwordx4 v[38:39], v[34:37], off nt
	v_pk_mul_f32 v[38:39], v[26:27], s[74:75] op_sel_hi:[1,0]
	v_pk_mul_f32 v[26:27], v[30:31], v[26:27]
	v_pk_mul_f32 v[36:37], v[30:31], v[30:31]
	v_pk_mul_f32 v[34:35], v[32:33], v[32:33]
	v_pk_fma_f32 v[36:37], v[36:37], s[22:23], 1.0 op_sel_hi:[1,0,0]
	v_exp_f32_e32 v38, v38
	v_pk_mul_f32 v[36:37], v[30:31], v[36:37]
	v_pk_fma_f32 v[30:31], v[34:35], s[22:23], 1.0 op_sel_hi:[1,0,0]
	v_pk_mul_f32 v[34:35], v[28:29], s[74:75] op_sel_hi:[1,0]
	v_pk_mul_f32 v[30:31], v[32:33], v[30:31]
	v_exp_f32_e32 v34, v34
	v_pk_mul_f32 v[30:31], v[30:31], s[84:85] op_sel_hi:[1,0]
	v_exp_f32_e32 v35, v35
; __device__ __forceinline__ unsigned cvt_pk_bf16(float lo, float hi) { unsigned r; asm volatile("v_cvt_pk_bf16_f32 %0, %1, %2" : "=v"(r) : "v"(lo), "v"(hi)); return r; }
; #define PG8_WAIT_V(n) asm volatile("s_waitcnt vmcnt(" #n ")" ::: "memory")
; #define PG8_BAR __builtin_amdgcn_s_barrier()
; template <class Epi>
; __device__ __forceinline__ void gemm_phase(LAS unsigned char* lds, const Gemm g, const StaticOrder& S_in, const Epi& E, int sw) {
;     ...
;         if (!has_next) break;
;         E.init(acc, nxt, sw);
;         cur = nxt; cA = nA; cB = nB; ++ui;
;     }
;     PG8_WAIT_V(0);
;     if (wr == 0) PG8_BAR;
;     EPI_ZERO_INIT
;     __device__ __forceinline__ void operator()(AccRef acc, const Unit& u, int sw) const {
;     ...
;         for (int ai = 0; ai < 2; ++ai)
; #pragma unroll
;             for (int m = 0; m < 4; ++m) { bf16_t* rowp = UG + (size_t)(row0 + ai * HALF + m * 16) * E + c0;
;                 float y[8];
; #pragma unroll
;                 for (int n = 0; n < 2; ++n)
; #pragma unroll
;                     for (int jp = 0; jp < 2; ++jp) {
;                         const f32x2 uu = (f32x2){acc[ai][0][m][n][2 * jp], acc[ai][0][m][n][2 * jp + 1]}, gg = (f32x2){acc[ai][1][m][n][2 * jp], acc[ai][1][m][n][2 * jp + 1]};
;                         const f32x2 za = (uu * uu * 0.044715f + 1.0f) * uu * (-1.44269504f * 1.59576912f), zg = gg * (-1.44269504f);
;                         f32x2 ea, eg; ea.x = __builtin_amdgcn_exp2f(za.x); ea.y = __builtin_amdgcn_exp2f(za.y); eg.x = __builtin_amdgcn_exp2f(zg.x); eg.y = __builtin_amdgcn_exp2f(zg.y);
;                         const f32x2 den = (ea + 1.0f) * (eg + 1.0f);
;                         f32x2 rc; rc.x = __builtin_amdgcn_rcpf(den.x); rc.y = __builtin_amdgcn_rcpf(den.y);
;                         const f32x2 yy = uu * gg * rc;
;                         y[4 * n + 2 * jp] = yy.x; y[4 * n + 2 * jp + 1] = yy.y; }
;                 u32x4 w; w.x = cvt_pk_bf16(y[0], y[1]); w.y = cvt_pk_bf16(y[2], y[3]); w.z = cvt_pk_bf16(y[4], y[5]); w.w = cvt_pk_bf16(y[6], y[7]);
;                 *(u32x4*)rowp = w; }
	v_exp_f32_e32 v30, v30
	v_exp_f32_e32 v31, v31
	v_pk_mul_f32 v[28:29], v[32:33], v[28:29]
	v_pk_mul_f32 v[32:33], v[22:23], v[22:23]
	v_pk_add_f32 v[34:35], v[34:35], 1.0 op_sel_hi:[1,0]
	v_pk_fma_f32 v[32:33], v[32:33], s[22:23], 1.0 op_sel_hi:[1,0,0]
	v_pk_add_f32 v[30:31], v[30:31], 1.0 op_sel_hi:[1,0]
	v_pk_mul_f32 v[32:33], v[22:23], v[32:33]
	v_pk_mul_f32 v[30:31], v[30:31], v[34:35]
	v_pk_mul_f32 v[32:33], v[32:33], s[84:85] op_sel_hi:[1,0]
	v_pk_mul_f32 v[34:35], v[18:19], s[74:75] op_sel_hi:[1,0]
	v_exp_f32_e32 v32, v32
	v_exp_f32_e32 v33, v33
	v_exp_f32_e32 v34, v34
	v_exp_f32_e32 v35, v35
	v_rcp_f32_e32 v30, v30
	v_pk_add_f32 v[32:33], v[32:33], 1.0 op_sel_hi:[1,0]
	v_rcp_f32_e32 v31, v31
	v_pk_add_f32 v[34:35], v[34:35], 1.0 op_sel_hi:[1,0]
	v_pk_mul_f32 v[18:19], v[22:23], v[18:19]
	v_pk_mul_f32 v[32:33], v[32:33], v[34:35]
	v_pk_mul_f32 v[28:29], v[28:29], v[30:31]
	v_rcp_f32_e32 v32, v32
	v_rcp_f32_e32 v33, v33
	v_pk_mul_f32 v[30:31], v[24:25], v[24:25]
	v_pk_mul_f32 v[36:37], v[36:37], s[84:85] op_sel_hi:[1,0]
	v_exp_f32_e32 v39, v39
	v_pk_mul_f32 v[22:23], v[18:19], v[32:33]
	v_pk_fma_f32 v[18:19], v[30:31], s[22:23], 1.0 op_sel_hi:[1,0,0]
	v_pk_mul_f32 v[30:31], v[20:21], s[74:75] op_sel_hi:[1,0]
	v_pk_mul_f32 v[18:19], v[24:25], v[18:19]
	v_exp_f32_e32 v36, v36
	v_pk_mul_f32 v[18:19], v[18:19], s[84:85] op_sel_hi:[1,0]
	v_exp_f32_e32 v37, v37
	v_exp_f32_e32 v18, v18
	v_exp_f32_e32 v19, v19
	v_exp_f32_e32 v30, v30
	v_exp_f32_e32 v31, v31
	v_pk_add_f32 v[36:37], v[36:37], 1.0 op_sel_hi:[1,0]
	v_pk_add_f32 v[38:39], v[38:39], 1.0 op_sel_hi:[1,0]
	v_pk_add_f32 v[18:19], v[18:19], 1.0 op_sel_hi:[1,0]
	v_pk_add_f32 v[30:31], v[30:31], 1.0 op_sel_hi:[1,0]
	v_pk_mul_f32 v[36:37], v[36:37], v[38:39]
	v_pk_mul_f32 v[18:19], v[18:19], v[30:31]
	v_rcp_f32_e32 v36, v36
	v_rcp_f32_e32 v37, v37
	v_rcp_f32_e32 v18, v18
	v_rcp_f32_e32 v19, v19
	v_pk_mul_f32 v[20:21], v[24:25], v[20:21]
	v_pk_mul_f32 v[26:27], v[26:27], v[36:37]
	v_pk_mul_f32 v[24:25], v[20:21], v[18:19]
	v_cvt_pk_bf16_f32 v18, v26, v27
	v_cvt_pk_bf16_f32 v19, v28, v29
	v_cvt_pk_bf16_f32 v20, v22, v23
	v_add_co_u32_e32 v22, vcc, s13, v114
	v_cvt_pk_bf16_f32 v21, v24, v25
	s_nop 1
	v_addc_co_u32_e32 v23, vcc, 0, v115, vcc
	global_store_dwordx4 v[22:23], v[18:21], off nt
	v_pk_mul_f32 v[22:23], v[10:11], s[74:75] op_sel_hi:[1,0]
	v_pk_mul_f32 v[10:11], v[14:15], v[10:11]
	v_pk_mul_f32 v[20:21], v[14:15], v[14:15]
	v_pk_mul_f32 v[18:19], v[16:17], v[16:17]
	v_pk_fma_f32 v[20:21], v[20:21], s[22:23], 1.0 op_sel_hi:[1,0,0]
	v_exp_f32_e32 v22, v22
	v_pk_mul_f32 v[20:21], v[14:15], v[20:21]
	v_pk_fma_f32 v[14:15], v[18:19], s[22:23], 1.0 op_sel_hi:[1,0,0]
	v_pk_mul_f32 v[18:19], v[12:13], s[74:75] op_sel_hi:[1,0]
	v_pk_mul_f32 v[14:15], v[16:17], v[14:15]
	v_exp_f32_e32 v18, v18
	v_pk_mul_f32 v[14:15], v[14:15], s[84:85] op_sel_hi:[1,0]
	v_exp_f32_e32 v19, v19
	v_exp_f32_e32 v14, v14
	v_exp_f32_e32 v15, v15
	v_pk_mul_f32 v[12:13], v[16:17], v[12:13]
	v_pk_mul_f32 v[16:17], v[6:7], v[6:7]
	v_pk_add_f32 v[18:19], v[18:19], 1.0 op_sel_hi:[1,0]
	v_pk_fma_f32 v[16:17], v[16:17], s[22:23], 1.0 op_sel_hi:[1,0,0]
	v_pk_add_f32 v[14:15], v[14:15], 1.0 op_sel_hi:[1,0]
	v_pk_mul_f32 v[16:17], v[6:7], v[16:17]
	v_pk_mul_f32 v[14:15], v[14:15], v[18:19]
	v_pk_mul_f32 v[16:17], v[16:17], s[84:85] op_sel_hi:[1,0]
	v_pk_mul_f32 v[18:19], v[2:3], s[74:75] op_sel_hi:[1,0]
	v_exp_f32_e32 v16, v16
	v_exp_f32_e32 v17, v17
	v_exp_f32_e32 v18, v18
	v_exp_f32_e32 v19, v19
	v_rcp_f32_e32 v14, v14
	v_pk_add_f32 v[16:17], v[16:17], 1.0 op_sel_hi:[1,0]
	v_rcp_f32_e32 v15, v15
	v_pk_add_f32 v[18:19], v[18:19], 1.0 op_sel_hi:[1,0]
	v_pk_mul_f32 v[2:3], v[6:7], v[2:3]
	v_pk_mul_f32 v[16:17], v[16:17], v[18:19]
	v_pk_mul_f32 v[12:13], v[12:13], v[14:15]
	v_rcp_f32_e32 v16, v16
	v_rcp_f32_e32 v17, v17
	v_pk_mul_f32 v[14:15], v[8:9], v[8:9]
	v_pk_mul_f32 v[20:21], v[20:21], s[84:85] op_sel_hi:[1,0]
	v_exp_f32_e32 v23, v23
	v_pk_mul_f32 v[6:7], v[2:3], v[16:17]
	v_pk_fma_f32 v[2:3], v[14:15], s[22:23], 1.0 op_sel_hi:[1,0,0]
	v_pk_mul_f32 v[14:15], v[4:5], s[74:75] op_sel_hi:[1,0]
	v_pk_mul_f32 v[2:3], v[8:9], v[2:3]
	v_exp_f32_e32 v20, v20
	v_pk_mul_f32 v[2:3], v[2:3], s[84:85] op_sel_hi:[1,0]
	v_exp_f32_e32 v21, v21
	v_exp_f32_e32 v2, v2
	v_exp_f32_e32 v3, v3
	v_exp_f32_e32 v14, v14
	v_exp_f32_e32 v15, v15
	v_pk_add_f32 v[20:21], v[20:21], 1.0 op_sel_hi:[1,0]
	v_pk_add_f32 v[22:23], v[22:23], 1.0 op_sel_hi:[1,0]
	v_pk_add_f32 v[2:3], v[2:3], 1.0 op_sel_hi:[1,0]
	v_pk_add_f32 v[14:15], v[14:15], 1.0 op_sel_hi:[1,0]
	v_pk_mul_f32 v[20:21], v[20:21], v[22:23]
	v_pk_mul_f32 v[2:3], v[2:3], v[14:15]
	v_rcp_f32_e32 v20, v20
	v_rcp_f32_e32 v21, v21
	v_rcp_f32_e32 v2, v2
	v_rcp_f32_e32 v3, v3
	v_pk_mul_f32 v[4:5], v[8:9], v[4:5]
	v_pk_mul_f32 v[10:11], v[10:11], v[20:21]
	v_pk_mul_f32 v[8:9], v[4:5], v[2:3]
	v_cvt_pk_bf16_f32 v2, v10, v11
	v_cvt_pk_bf16_f32 v3, v12, v13
	v_cvt_pk_bf16_f32 v4, v6, v7
	v_add_co_u32_e32 v6, vcc, 0x80c00, v114
	v_cvt_pk_bf16_f32 v5, v8, v9
	s_nop 1
	v_addc_co_u32_e32 v7, vcc, 0, v115, vcc
	global_store_dwordx4 v[6:7], v[2:5], off nt
	s_and_b64 vcc, exec, s[4:5]
	s_mov_b32 s50, s12
	s_mov_b32 s22, s16
	s_mov_b64 s[26:27], s[20:21]
	s_mov_b64 s[24:25], s[18:19]
	s_cbranch_vccz .LBB0_753
	s_waitcnt vmcnt(0)
	s_cmpk_gt_u32 s36, 0xff
	s_cbranch_scc1 .LBB0_760
	s_barrier
